# S5 prompt pass 0 without LDS: token-strided u rows give each lane a 16-token run, Horner in registers, quads combined once
# speedup vs baseline: 1.0627x; 1.0057x over previous
.LBB0_321:
	s_and_b32 s48, s47, 63
	s_lshl_b32 s0, s48, 2
	v_readlane_b32 s80, v242, 37
	v_mov_b32_e32 v3, v0
	v_mov_b32_e32 v4, s0
	v_readlane_b32 s84, v242, 41
	v_readlane_b32 s85, v242, 42
	s_lshl_b32 s18, s48, 6
	s_waitcnt vmcnt(0)
	v_and_b32_e32 v58, 63, v3
	v_readlane_b32 s82, v242, 39
	v_readlane_b32 s83, v242, 40
	global_load_dword v6, v4, s[84:85]
	v_or_b32_e32 v4, s18, v58
	v_lshlrev_b32_e32 v5, 2, v4
	v_readlane_b32 s81, v242, 38
	s_nop 0
	global_load_dword v4, v5, s[82:83]
	s_nop 2
	global_load_dword v5, v5, s[80:81]
	s_brev_b32 s0, 18
	v_readlane_b32 s86, v242, 43
	v_readlane_b32 s87, v242, 44
	v_readlane_b32 s88, v242, 45
	v_readlane_b32 s89, v242, 46
	v_readlane_b32 s90, v242, 47
	v_readlane_b32 s91, v242, 48
	v_readlane_b32 s92, v242, 49
	v_readlane_b32 s93, v242, 50
	v_readlane_b32 s94, v242, 51
	v_readlane_b32 s95, v242, 52
	v_and_b32_e32 v140, 15, v58
	v_lshrrev_b32_e32 v141, 4, v58
	s_lshl_b32 s26, s48, 12
	v_lshlrev_b32_e32 v131, 6, v140
	v_lshl_add_u32 v131, v141, 5, v131
	v_add_u32_e32 v131, s26, v131
	v_lshlrev_b32_e32 v240, 8, v140
	v_lshl_add_u32 v240, v141, 4, v240
	v_add_u32_e32 v240, s26, v240
	s_ashr_i32 s27, s47, 6
	s_lshl_b32 s27, s27, 11
	v_lshrrev_b32_e32 v218, 6, v3
	v_lshl_add_u32 v218, v218, 8, v140
	v_add_u32_e32 v218, s27, v218
	s_movk_i32 s27, 0x2400
	v_mul_u32_u24_e32 v218, s27, v218
	s_lshl_b32 s27, s48, 5
	s_add_u32 s27, s27, 0x1c00
	v_lshl_add_u32 v218, v141, 4, v218
	v_add_u32_e32 v218, s27, v218
	v_mov_b32_e32 v219, 0
	v_lshl_add_u64 v[84:85], v[218:219], 0, s[60:61]
	v_lshrrev_b32_e32 v218, 2, v140
	v_mul_u32_u24_e32 v218, 0x1b000, v218
	v_lshl_add_u64 v[182:183], v[84:85], 0, v[218:219]
	s_mov_b32 exec_lo, -1
	s_mov_b32 exec_hi, 0
	global_load_dwordx4 v[186:189], v131, s[86:87] offset:0
	global_load_dwordx4 v[190:193], v131, s[86:87] offset:16
	global_load_dwordx4 v[194:197], v131, s[88:89] offset:0
	global_load_dwordx4 v[198:201], v131, s[88:89] offset:16
	global_load_dwordx4 v[202:205], v131, s[86:87] offset:1024
	global_load_dwordx4 v[206:209], v131, s[86:87] offset:1040
	global_load_dwordx4 v[210:213], v131, s[88:89] offset:1024
	global_load_dwordx4 v[214:217], v131, s[88:89] offset:1040
	global_load_dwordx4 v[220:223], v131, s[86:87] offset:2048
	global_load_dwordx4 v[224:227], v131, s[86:87] offset:2064
	global_load_dwordx4 v[228:231], v131, s[88:89] offset:2048
	global_load_dwordx4 v[232:235], v131, s[88:89] offset:2064
	global_load_dwordx4 v[236:239], v131, s[86:87] offset:3072
	global_load_dwordx4 v[154:157], v131, s[86:87] offset:3088
	global_load_dwordx4 v[158:161], v131, s[88:89] offset:3072
	global_load_dwordx4 v[170:173], v131, s[88:89] offset:3088
	s_mov_b64 exec, -1
	global_load_dwordx4 v[142:145], v240, s[90:91] offset:0
	global_load_dwordx4 v[146:149], v240, s[90:91] offset:64
	global_load_dwordx4 v[150:153], v240, s[90:91] offset:128
	global_load_dwordx4 v[162:165], v240, s[90:91] offset:192
	global_load_dwordx4 v[166:169], v240, s[92:93] offset:0
	global_load_dwordx4 v[174:177], v240, s[92:93] offset:64
	global_load_dwordx4 v[178:181], v240, s[92:93] offset:128
	global_load_dwordx4 v[104:107], v240, s[92:93] offset:192
	s_waitcnt vmcnt(26)
	v_mul_f32_e32 v7, 0x3fb8aa3b, v6
	v_fma_f32 v8, v6, s28, -v7
	v_rndne_f32_e32 v9, v7
	v_fmac_f32_e32 v8, 0x32a5705f, v6
	v_sub_f32_e32 v7, v7, v9
	v_add_f32_e32 v7, v7, v8
	v_cvt_i32_f32_e32 v9, v9
	v_exp_f32_e32 v7, v7
	v_cmp_ngt_f32_e32 vcc, s29, v6
	v_ldexp_f32 v7, v7, v9
	s_nop 0
	v_cndmask_b32_e32 v7, 0, v7, vcc
	v_cmp_nlt_f32_e32 vcc, s30, v6
	s_nop 1
	v_cndmask_b32_e32 v8, v118, v7, vcc
	s_waitcnt vmcnt(25)
	v_mul_f32_e32 v6, v4, v8
	v_and_b32_e32 v7, 0x7fffffff, v6
	v_lshrrev_b32_e32 v9, 23, v7
	v_and_b32_e32 v10, 0x7fffff, v7
	v_cmp_nlt_f32_e64 s[8:9], |v6|, s0
	v_add_u32_e32 v12, 0xffffff88, v9
	v_or_b32_e32 v11, 0x800000, v10
	s_and_saveexec_b64 s[0:1], s[8:9]
	s_xor_b64 s[16:17], exec, s[0:1]
	s_cbranch_execz .LBB0_323
	v_mad_u64_u32 v[14:15], s[6:7], v11, s31, 0
	v_mov_b32_e32 v16, v15
	v_mov_b32_e32 v17, v2
	v_mad_u64_u32 v[16:17], s[6:7], v11, s33, v[16:17]
	v_mov_b32_e32 v18, v17
	v_mov_b32_e32 v19, v2
	v_mad_u64_u32 v[18:19], s[6:7], v11, s34, v[18:19]
	v_cmp_lt_u32_e32 vcc, 63, v12
	v_mov_b32_e32 v20, v19
	v_mov_b32_e32 v21, v2
	v_cndmask_b32_e32 v9, 0, v121, vcc
	v_mad_u64_u32 v[20:21], s[6:7], v11, s35, v[20:21]
	v_add_u32_e32 v9, v9, v12
	v_mov_b32_e32 v22, v21
	v_mov_b32_e32 v23, v2
	v_cmp_lt_u32_e64 s[0:1], 31, v9
	v_mad_u64_u32 v[22:23], s[6:7], v11, s36, v[22:23]
	s_nop 0
	v_cndmask_b32_e64 v10, 0, v122, s[0:1]
	v_mov_b32_e32 v24, v23
	v_mov_b32_e32 v25, v2
	v_add_u32_e32 v9, v10, v9
	v_mad_u64_u32 v[24:25], s[6:7], v11, s37, v[24:25]
	v_cmp_lt_u32_e64 s[4:5], 31, v9
	v_mov_b32_e32 v26, v25
	v_mov_b32_e32 v27, v2
	v_cndmask_b32_e64 v10, 0, v122, s[4:5]
	v_mad_u64_u32 v[26:27], s[6:7], v11, s38, v[26:27]
	v_add_u32_e32 v9, v10, v9
	v_cndmask_b32_e32 v10, v24, v20, vcc
	v_cndmask_b32_e32 v13, v26, v22, vcc
	v_cndmask_b32_e32 v17, v27, v24, vcc
	v_cndmask_b32_e64 v15, v13, v10, s[0:1]
	v_cndmask_b32_e64 v13, v17, v13, s[0:1]
	v_cndmask_b32_e32 v17, v22, v18, vcc
	v_cndmask_b32_e64 v10, v10, v17, s[0:1]
	v_cndmask_b32_e64 v13, v13, v15, s[4:5]
	v_cndmask_b32_e64 v15, v15, v10, s[4:5]
	v_sub_u32_e32 v19, 32, v9
	v_alignbit_b32 v21, v13, v15, v19
	v_cmp_eq_u32_e64 s[6:7], 0, v9
	v_cndmask_b32_e32 v14, v18, v14, vcc
	s_nop 0
	v_cndmask_b32_e64 v9, v21, v13, s[6:7]
	v_cndmask_b32_e32 v13, v20, v16, vcc
	v_cndmask_b32_e64 v16, v17, v13, s[0:1]
	v_cndmask_b32_e64 v10, v10, v16, s[4:5]
	v_alignbit_b32 v17, v15, v10, v19
	v_cndmask_b32_e64 v13, v13, v14, s[0:1]
	v_cndmask_b32_e64 v15, v17, v15, s[6:7]
	v_bfe_u32 v21, v9, 29, 1
	v_cndmask_b32_e64 v13, v16, v13, s[4:5]
	v_alignbit_b32 v17, v9, v15, 30
	v_sub_u32_e32 v22, 0, v21
	v_alignbit_b32 v14, v10, v13, v19
	v_xor_b32_e32 v17, v17, v22
	v_cndmask_b32_e64 v10, v14, v10, s[6:7]
	v_alignbit_b32 v14, v15, v10, 30
	v_ffbh_u32_e32 v15, v17
	v_min_u32_e32 v15, 32, v15
	v_alignbit_b32 v10, v10, v13, 30
	v_xor_b32_e32 v14, v14, v22
	v_sub_u32_e32 v16, 31, v15
	v_xor_b32_e32 v10, v10, v22
	v_alignbit_b32 v17, v17, v14, v16
	v_alignbit_b32 v10, v14, v10, v16
	v_alignbit_b32 v13, v17, v10, 9
	v_ffbh_u32_e32 v14, v13
	v_min_u32_e32 v14, 32, v14
	v_lshrrev_b32_e32 v20, 29, v9
	v_not_b32_e32 v16, v14
	v_alignbit_b32 v10, v13, v10, v16
	v_lshlrev_b32_e32 v13, 31, v20
	v_or_b32_e32 v16, 0x33000000, v13
	v_add_lshl_u32 v14, v14, v15, 23
	v_lshrrev_b32_e32 v10, 9, v10
	v_sub_u32_e32 v14, v16, v14
	v_or_b32_e32 v13, 0.5, v13
	v_lshlrev_b32_e32 v15, 23, v15
	v_or_b32_e32 v10, v14, v10
	v_lshrrev_b32_e32 v14, 9, v17
	v_sub_u32_e32 v13, v13, v15
	v_or_b32_e32 v13, v14, v13
	v_mul_f32_e32 v14, 0x3fc90fda, v13
	v_fma_f32 v15, v13, s39, -v14
	v_fmac_f32_e32 v15, 0x33a22168, v13
	v_fmac_f32_e32 v15, 0x3fc90fda, v10
	v_lshrrev_b32_e32 v9, 30, v9
	v_add_f32_e32 v10, v14, v15
	v_add_u32_e32 v9, v21, v9

.LBB0_329:
	s_or_b64 exec, exec, s[0:1]
	s_waitcnt vmcnt(24)
	v_mul_f32_e32 v8, v5, v8
	v_mul_f32_e32 v11, 0x3fb8aa3b, v8
	v_fma_f32 v12, v8, s28, -v11
	v_rndne_f32_e32 v15, v11
	v_fmac_f32_e32 v12, 0x32a5705f, v8
	v_sub_f32_e32 v11, v11, v15
	v_add_f32_e32 v11, v11, v12
	v_cvt_i32_f32_e32 v12, v15
	v_exp_f32_e32 v11, v11
	v_cmp_ngt_f32_e32 vcc, s29, v8
	s_brev_b32 s0, 1
	v_ashrrev_i32_e32 v76, 6, v3
	v_ldexp_f32 v11, v11, v12
	v_cndmask_b32_e32 v11, 0, v11, vcc
	v_cmp_nlt_f32_e32 vcc, s30, v8
	v_mul_f32_e32 v8, v10, v10
	v_and_b32_e32 v59, 15, v3
	v_cndmask_b32_e32 v42, v118, v11, vcc
	v_fmamk_f32 v11, v8, 0xb94c1982, v119
	v_fmaak_f32 v11, v8, v11, 0xbe2aaa9d
	v_mul_f32_e32 v11, v8, v11
	v_fmac_f32_e32 v10, v10, v11
	v_fmamk_f32 v11, v8, 0x37d75334, v120
	v_fmaak_f32 v11, v8, v11, 0x3d2aabf7
	v_fmaak_f32 v11, v8, v11, 0xbf000004
	v_fma_f32 v8, v8, v11, 1.0
	v_and_b32_e32 v11, 1, v9
	v_cmp_eq_u32_e32 vcc, 0, v11
	v_lshlrev_b32_e32 v9, 30, v9
	v_lshl_add_u32 v11, v76, 9, s41
	v_cndmask_b32_e64 v8, -v10, v8, vcc
	v_bitop3_b32 v8, v9, v8, s0 bitop3:0x6c
	s_movk_i32 s0, 0x1f8
	v_cmp_class_f32_e64 vcc, v6, s0
	v_xor_b32_e32 v6, v7, v6
	v_mul_f32_e32 v7, v4, v4
	v_cndmask_b32_e32 v43, v123, v8, vcc
	v_mul_f32_e32 v8, v14, v14
	v_fmamk_f32 v9, v8, 0xb94c1982, v119
	v_fmaak_f32 v9, v8, v9, 0xbe2aaa9d
	v_mul_f32_e32 v9, v8, v9
	v_fmac_f32_e32 v14, v14, v9
	v_fmamk_f32 v9, v8, 0x37d75334, v120
	v_fmaak_f32 v9, v8, v9, 0x3d2aabf7
	v_fmaak_f32 v9, v8, v9, 0xbf000004
	v_fma_f32 v8, v8, v9, 1.0
	v_and_b32_e32 v9, 1, v13
	v_cmp_eq_u32_e64 s[0:1], 0, v9
	v_lshlrev_b32_e32 v9, 30, v13
	v_and_b32_e32 v9, 0x80000000, v9
	v_cndmask_b32_e64 v8, v8, v14, s[0:1]
	v_xor_b32_e32 v6, v6, v9
	v_xor_b32_e32 v6, v6, v8
	v_cndmask_b32_e32 v6, v123, v6, vcc
	v_mul_f32_e32 v78, v42, v6
	v_fma_f32 v6, v42, v43, -1.0
	v_mul_f32_e32 v8, v4, v78
	v_fmac_f32_e32 v7, v5, v5
	v_fmac_f32_e32 v8, v5, v6
	v_div_scale_f32 v9, s[0:1], v7, v7, v8
	v_rcp_f32_e32 v10, v9
	v_mul_f32_e32 v4, v4, v6
	v_fma_f32 v4, v5, v78, -v4
	v_div_scale_f32 v5, s[0:1], v7, v7, v4
	v_fma_f32 v12, -v9, v10, 1.0
	v_fmac_f32_e32 v10, v12, v10
	v_div_scale_f32 v12, vcc, v8, v7, v8
	v_mul_f32_e32 v13, v12, v10
	v_rcp_f32_e32 v6, v5
	v_fma_f32 v14, -v9, v13, v12
	v_fmac_f32_e32 v13, v14, v10
	v_fma_f32 v9, -v9, v13, v12
	v_div_fmas_f32 v9, v9, v10, v13
	v_fma_f32 v10, -v5, v6, 1.0
	v_fmac_f32_e32 v6, v10, v6
	v_div_scale_f32 v10, vcc, v4, v7, v4
	v_mul_f32_e32 v12, v10, v6
	v_fma_f32 v13, -v5, v12, v10
	v_fmac_f32_e32 v12, v13, v6
	v_fma_f32 v5, -v5, v12, v10
	v_div_fmas_f32 v5, v5, v6, v12
	v_div_fixup_f32 v8, v9, v7, v8
	v_lshl_add_u32 v9, v58, 2, v11
	v_div_fixup_f32 v4, v5, v7, v4
	ds_write2st64_b32 v9, v8, v4 offset1:1
	v_lshrrev_b32_e32 v60, 4, v58
	s_waitcnt lgkmcnt(0)
	v_lshl_add_u32 v44, v59, 2, v11
	v_mov_b32_e32 v6, 0
	v_mov_b32_e32 v7, 0
	v_mov_b32_e32 v8, 0
	v_mov_b32_e32 v9, 0
	v_mov_b32_e32 v10, 0
	v_mov_b32_e32 v11, 0
	v_mov_b32_e32 v12, 0
	v_mov_b32_e32 v13, 0
	v_mov_b32_e32 v14, 0
	v_mov_b32_e32 v15, 0
	v_mov_b32_e32 v16, 0
	v_mov_b32_e32 v17, 0
	v_mov_b32_e32 v18, 0
	v_mov_b32_e32 v19, 0
	v_mov_b32_e32 v20, 0
	v_mov_b32_e32 v21, 0
	v_mov_b32_e32 v22, 0
	v_mov_b32_e32 v23, 0
	v_mov_b32_e32 v24, 0
	v_mov_b32_e32 v25, 0
	v_mov_b32_e32 v26, 0
	v_mov_b32_e32 v27, 0
	v_mov_b32_e32 v28, 0
	v_mov_b32_e32 v29, 0
	v_mov_b32_e32 v30, 0
	v_mov_b32_e32 v31, 0
	v_mov_b32_e32 v32, 0
	v_mov_b32_e32 v33, 0
	v_mov_b32_e32 v34, 0
	v_mov_b32_e32 v35, 0
	v_mov_b32_e32 v36, 0
	v_mov_b32_e32 v37, 0
	s_waitcnt vmcnt(8)
	s_mov_b32 exec_lo, -1
	s_mov_b32 exec_hi, 0
	ds_read2_b32 v[4:5], v44 offset0:0 offset1:64
	s_waitcnt lgkmcnt(0)
	v_mul_f32_e32 v62, v194, v5
	v_mul_f32_e32 v63, v195, v5
	v_mul_f32_e32 v64, v196, v5
	v_mul_f32_e32 v65, v197, v5
	v_mul_f32_e32 v66, v198, v5
	v_mul_f32_e32 v67, v199, v5
	v_mul_f32_e32 v68, v200, v5
	v_mul_f32_e32 v69, v201, v5
	v_fma_f32 v62, v186, v4, -v62
	v_fma_f32 v63, v187, v4, -v63
	v_fma_f32 v64, v188, v4, -v64
	v_fma_f32 v65, v189, v4, -v65
	v_fma_f32 v66, v190, v4, -v66
	v_fma_f32 v67, v191, v4, -v67
	v_fma_f32 v68, v192, v4, -v68
	v_fma_f32 v69, v193, v4, -v69
	v_cvt_pk_bf16_f32 v10, v62, v63
	v_cvt_pk_bf16_f32 v11, v64, v65
	v_cvt_pk_bf16_f32 v12, v66, v67
	v_cvt_pk_bf16_f32 v13, v68, v69
	v_mul_f32_e32 v194, v194, v4
	v_mul_f32_e32 v195, v195, v4
	v_mul_f32_e32 v196, v196, v4
	v_mul_f32_e32 v197, v197, v4
	v_mul_f32_e32 v198, v198, v4
	v_mul_f32_e32 v199, v199, v4
	v_mul_f32_e32 v200, v200, v4
	v_mul_f32_e32 v201, v201, v4
	v_fmac_f32_e32 v194, v186, v5
	v_fmac_f32_e32 v195, v187, v5
	v_fmac_f32_e32 v196, v188, v5
	v_fmac_f32_e32 v197, v189, v5
	v_fmac_f32_e32 v198, v190, v5
	v_fmac_f32_e32 v199, v191, v5
	v_fmac_f32_e32 v200, v192, v5
	v_fmac_f32_e32 v201, v193, v5
	v_cvt_pk_bf16_f32 v26, v194, v195
	v_cvt_pk_bf16_f32 v27, v196, v197
	v_cvt_pk_bf16_f32 v28, v198, v199
	v_cvt_pk_bf16_f32 v29, v200, v201
	ds_read2_b32 v[4:5], v44 offset0:16 offset1:80
	s_waitcnt lgkmcnt(0)
	v_mul_f32_e32 v62, v210, v5
	v_mul_f32_e32 v63, v211, v5
	v_mul_f32_e32 v64, v212, v5
	v_mul_f32_e32 v65, v213, v5
	v_mul_f32_e32 v66, v214, v5
	v_mul_f32_e32 v67, v215, v5
	v_mul_f32_e32 v68, v216, v5
	v_mul_f32_e32 v69, v217, v5
	v_fma_f32 v62, v202, v4, -v62
	v_fma_f32 v63, v203, v4, -v63
	v_fma_f32 v64, v204, v4, -v64
	v_fma_f32 v65, v205, v4, -v65
	v_fma_f32 v66, v206, v4, -v66
	v_fma_f32 v67, v207, v4, -v67
	v_fma_f32 v68, v208, v4, -v68
	v_fma_f32 v69, v209, v4, -v69
	v_cvt_pk_bf16_f32 v6, v62, v63
	v_cvt_pk_bf16_f32 v7, v64, v65
	v_cvt_pk_bf16_f32 v8, v66, v67
	v_cvt_pk_bf16_f32 v9, v68, v69
	v_mul_f32_e32 v210, v210, v4
	v_mul_f32_e32 v211, v211, v4
	v_mul_f32_e32 v212, v212, v4
	v_mul_f32_e32 v213, v213, v4
	v_mul_f32_e32 v214, v214, v4
	v_mul_f32_e32 v215, v215, v4
	v_mul_f32_e32 v216, v216, v4
	v_mul_f32_e32 v217, v217, v4
	v_fmac_f32_e32 v210, v202, v5
	v_fmac_f32_e32 v211, v203, v5
	v_fmac_f32_e32 v212, v204, v5
	v_fmac_f32_e32 v213, v205, v5
	v_fmac_f32_e32 v214, v206, v5
	v_fmac_f32_e32 v215, v207, v5
	v_fmac_f32_e32 v216, v208, v5
	v_fmac_f32_e32 v217, v209, v5
	v_cvt_pk_bf16_f32 v22, v210, v211
	v_cvt_pk_bf16_f32 v23, v212, v213
	v_cvt_pk_bf16_f32 v24, v214, v215
	v_cvt_pk_bf16_f32 v25, v216, v217
	ds_read2_b32 v[4:5], v44 offset0:32 offset1:96
	s_waitcnt lgkmcnt(0)
	v_mul_f32_e32 v62, v228, v5
	v_mul_f32_e32 v63, v229, v5
	v_mul_f32_e32 v64, v230, v5
	v_mul_f32_e32 v65, v231, v5
	v_mul_f32_e32 v66, v232, v5
	v_mul_f32_e32 v67, v233, v5
	v_mul_f32_e32 v68, v234, v5
	v_mul_f32_e32 v69, v235, v5
	v_fma_f32 v62, v220, v4, -v62
	v_fma_f32 v63, v221, v4, -v63
	v_fma_f32 v64, v222, v4, -v64
	v_fma_f32 v65, v223, v4, -v65
	v_fma_f32 v66, v224, v4, -v66
	v_fma_f32 v67, v225, v4, -v67
	v_fma_f32 v68, v226, v4, -v68
	v_fma_f32 v69, v227, v4, -v69
	v_cvt_pk_bf16_f32 v18, v62, v63
	v_cvt_pk_bf16_f32 v19, v64, v65
	v_cvt_pk_bf16_f32 v20, v66, v67
	v_cvt_pk_bf16_f32 v21, v68, v69
	v_mul_f32_e32 v228, v228, v4
	v_mul_f32_e32 v229, v229, v4
	v_mul_f32_e32 v230, v230, v4
	v_mul_f32_e32 v231, v231, v4
	v_mul_f32_e32 v232, v232, v4
	v_mul_f32_e32 v233, v233, v4
	v_mul_f32_e32 v234, v234, v4
	v_mul_f32_e32 v235, v235, v4
	v_fmac_f32_e32 v228, v220, v5
	v_fmac_f32_e32 v229, v221, v5
	v_fmac_f32_e32 v230, v222, v5
	v_fmac_f32_e32 v231, v223, v5
	v_fmac_f32_e32 v232, v224, v5
	v_fmac_f32_e32 v233, v225, v5
	v_fmac_f32_e32 v234, v226, v5
	v_fmac_f32_e32 v235, v227, v5
	v_cvt_pk_bf16_f32 v34, v228, v229
	v_cvt_pk_bf16_f32 v35, v230, v231
	v_cvt_pk_bf16_f32 v36, v232, v233
	v_cvt_pk_bf16_f32 v37, v234, v235
	ds_read2_b32 v[4:5], v44 offset0:48 offset1:112
	s_waitcnt lgkmcnt(0)
	v_mul_f32_e32 v62, v158, v5
	v_mul_f32_e32 v63, v159, v5
	v_mul_f32_e32 v64, v160, v5
	v_mul_f32_e32 v65, v161, v5
	v_mul_f32_e32 v66, v170, v5
	v_mul_f32_e32 v67, v171, v5
	v_mul_f32_e32 v68, v172, v5
	v_mul_f32_e32 v69, v173, v5
	v_fma_f32 v62, v236, v4, -v62
	v_fma_f32 v63, v237, v4, -v63
	v_fma_f32 v64, v238, v4, -v64
	v_fma_f32 v65, v239, v4, -v65
	v_fma_f32 v66, v154, v4, -v66
	v_fma_f32 v67, v155, v4, -v67
	v_fma_f32 v68, v156, v4, -v68
	v_fma_f32 v69, v157, v4, -v69
	v_cvt_pk_bf16_f32 v14, v62, v63
	v_cvt_pk_bf16_f32 v15, v64, v65
	v_cvt_pk_bf16_f32 v16, v66, v67
	v_cvt_pk_bf16_f32 v17, v68, v69
	v_mul_f32_e32 v158, v158, v4
	v_mul_f32_e32 v159, v159, v4
	v_mul_f32_e32 v160, v160, v4
	v_mul_f32_e32 v161, v161, v4
	v_mul_f32_e32 v170, v170, v4
	v_mul_f32_e32 v171, v171, v4
	v_mul_f32_e32 v172, v172, v4
	v_mul_f32_e32 v173, v173, v4
	v_fmac_f32_e32 v158, v236, v5
	v_fmac_f32_e32 v159, v237, v5
	v_fmac_f32_e32 v160, v238, v5
	v_fmac_f32_e32 v161, v239, v5
	v_fmac_f32_e32 v170, v154, v5
	v_fmac_f32_e32 v171, v155, v5
	v_fmac_f32_e32 v172, v156, v5
	v_fmac_f32_e32 v173, v157, v5
	v_cvt_pk_bf16_f32 v30, v158, v159
	v_cvt_pk_bf16_f32 v31, v160, v161
	v_cvt_pk_bf16_f32 v32, v170, v171
	v_cvt_pk_bf16_f32 v33, v172, v173
	s_mov_b64 exec, -1
	v_mov_b32_e32 v186, 0
	v_mov_b32_e32 v187, 0
	v_mov_b32_e32 v188, 0
	v_mov_b32_e32 v189, 0
	v_mov_b32_e32 v190, 0
	v_mov_b32_e32 v191, 0
	v_mov_b32_e32 v192, 0
	v_mov_b32_e32 v193, 0
	v_mov_b32_e32 v194, 0
	v_mov_b32_e32 v195, 0
	v_mov_b32_e32 v196, 0
	v_mov_b32_e32 v197, 0
	v_mov_b32_e32 v198, 0
	v_mov_b32_e32 v199, 0
	v_mov_b32_e32 v200, 0
	v_mov_b32_e32 v201, 0
	v_mov_b32_e32 v202, 0
	v_mov_b32_e32 v203, 0
	v_mov_b32_e32 v204, 0
	v_mov_b32_e32 v205, 0
	v_mov_b32_e32 v206, 0
	v_mov_b32_e32 v207, 0
	v_mov_b32_e32 v208, 0
	v_mov_b32_e32 v209, 0
	v_mov_b32_e32 v210, 0
	v_mov_b32_e32 v211, 0
	v_mov_b32_e32 v212, 0
	v_mov_b32_e32 v213, 0
	v_mov_b32_e32 v214, 0
	v_mov_b32_e32 v215, 0
	v_mov_b32_e32 v216, 0
	v_mov_b32_e32 v217, 0
	s_mov_b32 exec_lo, -1
	s_mov_b32 exec_hi, 0
	global_load_dwordx4 v[186:189], v[182:183], off
	s_mov_b64 s[26:27], 0x9000
	v_lshl_add_u64 v[4:5], v[182:183], 0, s[26:27]
	global_load_dwordx4 v[190:193], v[4:5], off
	s_add_u32 s26, s26, 0x9000
	s_addc_u32 s27, s27, 0
	v_lshl_add_u64 v[4:5], v[182:183], 0, s[26:27]
	global_load_dwordx4 v[194:197], v[4:5], off
	s_add_u32 s26, s26, 0x9000
	s_addc_u32 s27, s27, 0
	v_lshl_add_u64 v[4:5], v[182:183], 0, s[26:27]
	global_load_dwordx4 v[198:201], v[4:5], off
	s_mov_b64 exec, -1
	s_lshl_b32 s0, s48, 12
	v_readlane_b32 s80, v242, 37
	v_lshlrev_b32_e32 v61, 3, v60
	v_lshl_or_b32 v4, v59, 8, s0
	v_mov_b32_e32 v5, v2
	v_readlane_b32 s90, v242, 47
	v_readlane_b32 s91, v242, 48
	v_readlane_b32 s92, v242, 49
	v_readlane_b32 s93, v242, 50
	v_lshl_add_u64 v[38:39], s[90:91], 0, v[4:5]
	v_lshlrev_b32_e32 v40, 1, v61
	v_mov_b32_e32 v41, v2
	v_lshl_add_u64 v[38:39], v[38:39], 0, v[40:41]
	v_lshl_add_u64 v[4:5], s[92:93], 0, v[4:5]
	v_lshl_add_u64 v[4:5], v[4:5], 0, v[40:41]
	s_ashr_i32 s16, s47, 6
	s_and_b32 s6, s46, 63
	s_movk_i32 s12, 0x2800
	s_ashr_i32 s17, s16, 31
	v_readlane_b32 s94, v242, 51
	v_mul_lo_u32 v56, v76, s12
	s_lshl_b32 s12, s6, 5
	s_lshl_b64 s[20:21], s[16:17], 11
	v_readlane_b32 s95, v242, 52
	v_lshlrev_b32_e32 v40, 7, v76
	v_ashrrev_i32_e32 v77, 31, v76
	s_add_u32 s18, s94, s18
	v_lshlrev_b32_e32 v41, 4, v60
	v_lshlrev_b32_e32 v82, 2, v58
	v_lshlrev_b64 v[38:39], 8, v[76:77]
	v_lshlrev_b32_e32 v40, 2, v40
	v_add_u32_e32 v74, 0, v56
	s_addc_u32 s19, s95, 0
	v_add3_u32 v77, s42, v40, v82
	v_add_u32_e32 v75, v74, v41
	v_lshl_add_u64 v[56:57], v[38:39], 0, s[20:21]
	global_load_dwordx4 v[38:41], v41, s[18:19]
	v_mov_b64_e32 v[4:5], s[60:61]
	v_or_b32_e32 v56, v56, v59
	v_mad_u64_u32 v[4:5], s[18:19], v56, s43, v[4:5]
	s_mov_b32 s7, s13
	s_lshl_b32 s6, s48, 5
	v_mad_i32_i24 v5, v57, s43, v5
	v_mul_f32_e32 v80, v42, v43
	v_mov_b32_e32 v43, v2
	v_lshlrev_b32_e32 v42, 1, v61
	v_lshl_add_u64 v[4:5], v[4:5], 0, s[6:7]
	v_lshl_add_u64 v[4:5], v[4:5], 0, v[42:43]
	v_lshl_add_u64 v[84:85], v[4:5], 0, s[14:15]
	v_cmp_lt_u32_e32 vcc, 31, v58
	v_cmp_gt_u32_e64 s[4:5], 32, v58
	v_mul_u32_u24_e32 v60, 0x280, v60
	v_cmp_eq_u32_e64 s[0:1], 7, v76
	v_cmp_lt_i32_e64 s[8:9], 0, v76
	v_mov_b32_e32 v81, v80
	v_mov_b32_e32 v79, v78
	v_add_u32_e32 v83, s44, v82
	s_mov_b64 s[20:21], -1
	s_mov_b64 s[22:23], 0
	s_xor_b64 s[18:19], vcc, -1
	v_readlane_b32 s81, v242, 38
	v_readlane_b32 s82, v242, 39
	v_readlane_b32 s83, v242, 40
	v_readlane_b32 s84, v242, 41
	v_readlane_b32 s85, v242, 42
	v_readlane_b32 s86, v242, 43
	v_readlane_b32 s87, v242, 44
	v_readlane_b32 s88, v242, 45
	v_readlane_b32 s89, v242, 46
	s_waitcnt vmcnt(5)
	v_cvt_pk_bf16_f32 v42, v142, -v166
	v_cvt_pk_bf16_f32 v43, v143, -v167
	v_cvt_pk_bf16_f32 v44, v144, -v168
	v_cvt_pk_bf16_f32 v45, v145, -v169
	v_cvt_pk_bf16_f32 v46, v146, -v174
	v_cvt_pk_bf16_f32 v47, v147, -v175
	v_cvt_pk_bf16_f32 v48, v148, -v176
	v_cvt_pk_bf16_f32 v49, v149, -v177
	v_cvt_pk_bf16_f32 v50, v150, -v178
	v_cvt_pk_bf16_f32 v51, v151, -v179
	v_cvt_pk_bf16_f32 v52, v152, -v180
	v_cvt_pk_bf16_f32 v53, v153, -v181
	v_cvt_pk_bf16_f32 v54, v162, -v104
	v_cvt_pk_bf16_f32 v55, v163, -v105
	v_cvt_pk_bf16_f32 v56, v164, -v106
	v_cvt_pk_bf16_f32 v57, v165, -v107
	v_add_f32_e32 v5, v80, v80
	v_mul_f32_e32 v4, v78, v78
	v_mul_f32_e32 v5, v5, v78
	v_mul_u32_u24_e32 v62, 0x50, v58
	v_fma_f32 v4, v80, v80, -v4
	v_mul_f32_e32 v58, v5, v5
	v_fma_f32 v58, v4, v4, -v58
	v_add_f32_e32 v4, v4, v4
	v_mul_f32_e32 v4, v5, v4
	v_mul_f32_e32 v5, v4, v4
	v_fma_f32 v5, v58, v58, -v5
	v_add_f32_e32 v58, v58, v58
	v_mul_f32_e32 v4, v4, v58
	v_mul_f32_e32 v58, v4, v4
	v_fma_f32 v58, v5, v5, -v58
	v_add_f32_e32 v5, v5, v5
	v_mul_f32_e32 v4, v4, v5
	v_mul_f32_e32 v5, v4, v4
	v_fma_f32 v5, v58, v58, -v5
	v_add_f32_e32 v58, v58, v58
	v_mul_f32_e32 v4, v4, v58
	v_mul_f32_e32 v58, v4, v4
	v_fma_f32 v58, v5, v5, -v58
	v_add_f32_e32 v5, v5, v5
	v_mul_f32_e32 v4, v4, v5
	v_mul_f32_e32 v5, v4, v4
	v_fma_f32 v5, v58, v58, -v5
	v_add_f32_e32 v58, v58, v58
	v_mul_f32_e32 v4, v4, v58
	v_mul_f32_e32 v58, v4, v4
	v_fma_f32 v86, v5, v5, -v58
	v_add_f32_e32 v5, v5, v5
	v_mul_f32_e32 v88, v4, v5
	v_mad_i64_i32 v[4:5], s[6:7], v76, s45, 0
	v_lshl_add_u32 v63, v59, 2, v74
	v_mul_u32_u24_e32 v64, 0x50, v59
	v_mad_i64_i32 v[4:5], s[6:7], s16, v127, v[4:5]
	v_mul_hi_u32_u24_e32 v58, 0x2400, v59
	v_mul_u32_u24_e32 v59, 0x2400, v59
	v_or_b32_e32 v5, v5, v58
	v_or_b32_e32 v4, v4, v59
	v_lshl_add_u64 v[4:5], v[4:5], 0, s[12:13]
	v_or_b32_e32 v58, v4, v61
	v_mov_b32_e32 v59, v5
	v_lshl_add_u64 v[94:95], s[2:3], 0, v[58:59]
	v_and_b32_e32 v58, 48, v3
	v_mov_b32_e32 v59, v2
	v_lshl_add_u64 v[4:5], v[4:5], 0, v[58:59]
	v_mov_b32_e32 v3, v2
	v_mov_b32_e32 v87, v86
	v_mov_b32_e32 v89, v88
	v_mov_b32_e32 v90, v80
	v_mov_b32_e32 v91, v78
	v_mov_b32_e32 v92, v78
	v_mov_b32_e32 v93, v80
	v_lshl_add_u64 v[96:97], s[10:11], 0, v[4:5]
	v_add_u32_e32 v128, v75, v64
	v_add_u32_e32 v129, v63, v60
	v_lshrrev_b32_e32 v185, 1, v60
	v_add_u32_e32 v185, v63, v185
	v_add_u32_e32 v130, v74, v62
	v_mov_b64_e32 v[98:99], v[2:3]
	s_branch .LBB0_347

.Ls5p_loop0:
	v_mbcnt_lo_u32_b32 v3, -1, 0
	v_mbcnt_hi_u32_b32 v3, -1, v3
	v_and_b32_e32 v131, 15, v3
	v_lshlrev_b32_e32 v131, 2, v131
	v_mov_b32_e32 v62, v80
	v_mov_b32_e32 v63, v78
	v_mul_f32_e32 v64, v63, v63
	v_mul_f32_e32 v65, v62, v63
	v_fma_f32 v62, v62, v62, -v64
	v_add_f32_e32 v63, v65, v65
	v_mul_f32_e32 v64, v63, v63
	v_mul_f32_e32 v65, v62, v63
	v_fma_f32 v62, v62, v62, -v64
	v_add_f32_e32 v63, v65, v65
	v_mul_f32_e32 v64, v63, v63
	v_mul_f32_e32 v65, v62, v63
	v_fma_f32 v62, v62, v62, -v64
	v_add_f32_e32 v63, v65, v65
	v_mul_f32_e32 v64, v63, v63
	v_mul_f32_e32 v65, v62, v63
	v_fma_f32 v62, v62, v62, -v64
	v_add_f32_e32 v63, v65, v65
	v_mov_b32_e32 v140, v62
	v_mov_b32_e32 v141, v63
	v_mul_f32_e32 v64, v63, v63
	v_mul_f32_e32 v65, v62, v63
	v_fma_f32 v62, v62, v62, -v64
	v_add_f32_e32 v63, v65, v65
	v_mul_f32_e32 v64, v63, v63
	v_mul_f32_e32 v65, v62, v63
	v_fma_f32 v62, v62, v62, -v64
	v_add_f32_e32 v63, v65, v65
	ds_bpermute_b32 v220, v131, v80
	ds_bpermute_b32 v221, v131, v78
	ds_bpermute_b32 v222, v131, v62
	ds_bpermute_b32 v223, v131, v63
	v_add_u32_e32 v4, 64, v131
	ds_bpermute_b32 v224, v4, v80
	ds_bpermute_b32 v225, v4, v78
	ds_bpermute_b32 v226, v4, v62
	ds_bpermute_b32 v227, v4, v63
	v_add_u32_e32 v4, 128, v131
	ds_bpermute_b32 v228, v4, v80
	ds_bpermute_b32 v229, v4, v78
	ds_bpermute_b32 v230, v4, v62
	ds_bpermute_b32 v231, v4, v63
	v_add_u32_e32 v4, 192, v131
	ds_bpermute_b32 v232, v4, v80
	ds_bpermute_b32 v233, v4, v78
	ds_bpermute_b32 v234, v4, v62
	ds_bpermute_b32 v235, v4, v63
	v_mov_b32_e32 v236, 0
	v_mov_b32_e32 v158, 0
	v_mov_b32_e32 v237, 0
	v_mov_b32_e32 v159, 0
	v_mov_b32_e32 v238, 0
	v_mov_b32_e32 v160, 0
	v_mov_b32_e32 v239, 0
	v_mov_b32_e32 v161, 0
	s_waitcnt lgkmcnt(0)
	v_xor_b32_e32 v170, 0x80000000, v221
	v_xor_b32_e32 v171, 0x80000000, v225
	v_xor_b32_e32 v172, 0x80000000, v229
	v_xor_b32_e32 v173, 0x80000000, v233
.Ls5p_sb0:
	s_cmp_lg_u32 s24, 0x1b0000
	s_cbranch_scc0 .Ls5p_nopf0
	s_add_u32 s26, s24, 0x90000
	s_addc_u32 s27, s25, 0
	s_mov_b64 exec, s[4:5]
	v_lshl_add_u64 v[4:5], v[182:183], 0, s[26:27]
	global_load_dwordx4 v[202:205], v[4:5], off
	s_add_u32 s26, s26, 0x9000
	s_addc_u32 s27, s27, 0
	v_lshl_add_u64 v[4:5], v[182:183], 0, s[26:27]
	global_load_dwordx4 v[206:209], v[4:5], off
	s_add_u32 s26, s26, 0x9000
	s_addc_u32 s27, s27, 0
	v_lshl_add_u64 v[4:5], v[182:183], 0, s[26:27]
	global_load_dwordx4 v[210:213], v[4:5], off
	s_add_u32 s26, s26, 0x9000
	s_addc_u32 s27, s27, 0
	v_lshl_add_u64 v[4:5], v[182:183], 0, s[26:27]
	global_load_dwordx4 v[214:217], v[4:5], off
	s_mov_b64 exec, -1
.Ls5p_nopf0:
	v_mfma_f32_16x16x32_bf16 v[66:69], v[186:189], v[10:13], 0
	v_mfma_f32_16x16x32_bf16 v[110:113], v[186:189], v[26:29], 0
	v_mfma_f32_16x16x32_bf16 v[70:73], v[190:193], v[10:13], 0
	v_mfma_f32_16x16x32_bf16 v[114:117], v[190:193], v[26:29], 0
	v_mfma_f32_16x16x32_bf16 v[102:105], v[194:197], v[10:13], 0
	v_mfma_f32_16x16x32_bf16 v[132:135], v[194:197], v[26:29], 0
	v_mfma_f32_16x16x32_bf16 v[106:109], v[198:201], v[10:13], 0
	v_mfma_f32_16x16x32_bf16 v[136:139], v[198:201], v[26:29], 0
	v_mfma_f32_16x16x32_bf16 v[142:145], v[186:189], v[6:9], 0
	v_mfma_f32_16x16x32_bf16 v[166:169], v[186:189], v[22:25], 0
	v_mfma_f32_16x16x32_bf16 v[146:149], v[190:193], v[6:9], 0
	v_mfma_f32_16x16x32_bf16 v[174:177], v[190:193], v[22:25], 0
	v_mfma_f32_16x16x32_bf16 v[150:153], v[194:197], v[6:9], 0
	v_mfma_f32_16x16x32_bf16 v[178:181], v[194:197], v[22:25], 0
	v_mfma_f32_16x16x32_bf16 v[162:165], v[198:201], v[6:9], 0
	v_mfma_f32_16x16x32_bf16 v[154:157], v[198:201], v[22:25], 0
	v_fmac_f32_e32 v67, v220, v66
	v_fmac_f32_e32 v111, v220, v110
	v_fmac_f32_e32 v67, v170, v110
	v_fmac_f32_e32 v111, v221, v66
	v_fmac_f32_e32 v68, v220, v67
	v_fmac_f32_e32 v112, v220, v111
	v_fmac_f32_e32 v68, v170, v111
	v_fmac_f32_e32 v112, v221, v67
	v_fmac_f32_e32 v69, v220, v68
	v_fmac_f32_e32 v113, v220, v112
	v_fmac_f32_e32 v69, v170, v112
	v_fmac_f32_e32 v113, v221, v68
	v_fmac_f32_e32 v70, v220, v69
	v_fmac_f32_e32 v114, v220, v113
	v_fmac_f32_e32 v70, v170, v113
	v_fmac_f32_e32 v114, v221, v69
	v_fmac_f32_e32 v71, v220, v70
	v_fmac_f32_e32 v115, v220, v114
	v_fmac_f32_e32 v71, v170, v114
	v_fmac_f32_e32 v115, v221, v70
	v_fmac_f32_e32 v72, v220, v71
	v_fmac_f32_e32 v116, v220, v115
	v_fmac_f32_e32 v72, v170, v115
	v_fmac_f32_e32 v116, v221, v71
	v_fmac_f32_e32 v73, v220, v72
	v_fmac_f32_e32 v117, v220, v116
	v_fmac_f32_e32 v73, v170, v116
	v_fmac_f32_e32 v117, v221, v72
	v_fmac_f32_e32 v102, v220, v73
	v_fmac_f32_e32 v132, v220, v117
	v_fmac_f32_e32 v102, v170, v117
	v_fmac_f32_e32 v132, v221, v73
	v_fmac_f32_e32 v103, v220, v102
	v_fmac_f32_e32 v133, v220, v132
	v_fmac_f32_e32 v103, v170, v132
	v_fmac_f32_e32 v133, v221, v102
	v_fmac_f32_e32 v104, v220, v103
	v_fmac_f32_e32 v134, v220, v133
	v_fmac_f32_e32 v104, v170, v133
	v_fmac_f32_e32 v134, v221, v103
	v_fmac_f32_e32 v105, v220, v104
	v_fmac_f32_e32 v135, v220, v134
	v_fmac_f32_e32 v105, v170, v134
	v_fmac_f32_e32 v135, v221, v104
	v_fmac_f32_e32 v106, v220, v105
	v_fmac_f32_e32 v136, v220, v135
	v_fmac_f32_e32 v106, v170, v135
	v_fmac_f32_e32 v136, v221, v105
	v_fmac_f32_e32 v107, v220, v106
	v_fmac_f32_e32 v137, v220, v136
	v_fmac_f32_e32 v107, v170, v136
	v_fmac_f32_e32 v137, v221, v106
	v_fmac_f32_e32 v108, v220, v107
	v_fmac_f32_e32 v138, v220, v137
	v_fmac_f32_e32 v108, v170, v137
	v_fmac_f32_e32 v138, v221, v107
	v_fmac_f32_e32 v109, v220, v108
	v_fmac_f32_e32 v139, v220, v138
	v_fmac_f32_e32 v109, v170, v138
	v_fmac_f32_e32 v139, v221, v108
	v_fmac_f32_e32 v109, v222, v236
	v_fmac_f32_e32 v139, v222, v158
	v_fma_f32 v109, -v223, v158, v109
	v_fmac_f32_e32 v139, v223, v236
	v_mov_b32_e32 v236, v109
	v_mov_b32_e32 v158, v139
	v_mfma_f32_16x16x32_bf16 v[66:69], v[186:189], v[18:21], 0
	v_mfma_f32_16x16x32_bf16 v[110:113], v[186:189], v[34:37], 0
	v_mfma_f32_16x16x32_bf16 v[70:73], v[190:193], v[18:21], 0
	v_mfma_f32_16x16x32_bf16 v[114:117], v[190:193], v[34:37], 0
	v_mfma_f32_16x16x32_bf16 v[102:105], v[194:197], v[18:21], 0
	v_mfma_f32_16x16x32_bf16 v[132:135], v[194:197], v[34:37], 0
	v_mfma_f32_16x16x32_bf16 v[106:109], v[198:201], v[18:21], 0
	v_mfma_f32_16x16x32_bf16 v[136:139], v[198:201], v[34:37], 0
	v_fmac_f32_e32 v143, v224, v142
	v_fmac_f32_e32 v167, v224, v166
	v_fmac_f32_e32 v143, v171, v166
	v_fmac_f32_e32 v167, v225, v142
	v_fmac_f32_e32 v144, v224, v143
	v_fmac_f32_e32 v168, v224, v167
	v_fmac_f32_e32 v144, v171, v167
	v_fmac_f32_e32 v168, v225, v143
	v_fmac_f32_e32 v145, v224, v144
	v_fmac_f32_e32 v169, v224, v168
	v_fmac_f32_e32 v145, v171, v168
	v_fmac_f32_e32 v169, v225, v144
	v_fmac_f32_e32 v146, v224, v145
	v_fmac_f32_e32 v174, v224, v169
	v_fmac_f32_e32 v146, v171, v169
	v_fmac_f32_e32 v174, v225, v145
	v_fmac_f32_e32 v147, v224, v146
	v_fmac_f32_e32 v175, v224, v174
	v_fmac_f32_e32 v147, v171, v174
	v_fmac_f32_e32 v175, v225, v146
	v_fmac_f32_e32 v148, v224, v147
	v_fmac_f32_e32 v176, v224, v175
	v_fmac_f32_e32 v148, v171, v175
	v_fmac_f32_e32 v176, v225, v147
	v_fmac_f32_e32 v149, v224, v148
	v_fmac_f32_e32 v177, v224, v176
	v_fmac_f32_e32 v149, v171, v176
	v_fmac_f32_e32 v177, v225, v148
	v_fmac_f32_e32 v150, v224, v149
	v_fmac_f32_e32 v178, v224, v177
	v_fmac_f32_e32 v150, v171, v177
	v_fmac_f32_e32 v178, v225, v149
	v_fmac_f32_e32 v151, v224, v150
	v_fmac_f32_e32 v179, v224, v178
	v_fmac_f32_e32 v151, v171, v178
	v_fmac_f32_e32 v179, v225, v150
	v_fmac_f32_e32 v152, v224, v151
	v_fmac_f32_e32 v180, v224, v179
	v_fmac_f32_e32 v152, v171, v179
	v_fmac_f32_e32 v180, v225, v151
	v_fmac_f32_e32 v153, v224, v152
	v_fmac_f32_e32 v181, v224, v180
	v_fmac_f32_e32 v153, v171, v180
	v_fmac_f32_e32 v181, v225, v152
	v_fmac_f32_e32 v162, v224, v153
	v_fmac_f32_e32 v154, v224, v181
	v_fmac_f32_e32 v162, v171, v181
	v_fmac_f32_e32 v154, v225, v153
	v_fmac_f32_e32 v163, v224, v162
	v_fmac_f32_e32 v155, v224, v154
	v_fmac_f32_e32 v163, v171, v154
	v_fmac_f32_e32 v155, v225, v162
	v_fmac_f32_e32 v164, v224, v163
	v_fmac_f32_e32 v156, v224, v155
	v_fmac_f32_e32 v164, v171, v155
	v_fmac_f32_e32 v156, v225, v163
	v_fmac_f32_e32 v165, v224, v164
	v_fmac_f32_e32 v157, v224, v156
	v_fmac_f32_e32 v165, v171, v156
	v_fmac_f32_e32 v157, v225, v164
	v_fmac_f32_e32 v165, v226, v237
	v_fmac_f32_e32 v157, v226, v159
	v_fma_f32 v165, -v227, v159, v165
	v_fmac_f32_e32 v157, v227, v237
	v_mov_b32_e32 v237, v165
	v_mov_b32_e32 v159, v157
	v_mfma_f32_16x16x32_bf16 v[142:145], v[186:189], v[14:17], 0
	v_mfma_f32_16x16x32_bf16 v[166:169], v[186:189], v[30:33], 0
	v_mfma_f32_16x16x32_bf16 v[146:149], v[190:193], v[14:17], 0
	v_mfma_f32_16x16x32_bf16 v[174:177], v[190:193], v[30:33], 0
	v_mfma_f32_16x16x32_bf16 v[150:153], v[194:197], v[14:17], 0
	v_mfma_f32_16x16x32_bf16 v[178:181], v[194:197], v[30:33], 0
	v_mfma_f32_16x16x32_bf16 v[162:165], v[198:201], v[14:17], 0
	v_mfma_f32_16x16x32_bf16 v[154:157], v[198:201], v[30:33], 0
	v_fmac_f32_e32 v67, v228, v66
	v_fmac_f32_e32 v111, v228, v110
	v_fmac_f32_e32 v67, v172, v110
	v_fmac_f32_e32 v111, v229, v66
	v_fmac_f32_e32 v68, v228, v67
	v_fmac_f32_e32 v112, v228, v111
	v_fmac_f32_e32 v68, v172, v111
	v_fmac_f32_e32 v112, v229, v67
	v_fmac_f32_e32 v69, v228, v68
	v_fmac_f32_e32 v113, v228, v112
	v_fmac_f32_e32 v69, v172, v112
	v_fmac_f32_e32 v113, v229, v68
	v_fmac_f32_e32 v70, v228, v69
	v_fmac_f32_e32 v114, v228, v113
	v_fmac_f32_e32 v70, v172, v113
	v_fmac_f32_e32 v114, v229, v69
	v_fmac_f32_e32 v71, v228, v70
	v_fmac_f32_e32 v115, v228, v114
	v_fmac_f32_e32 v71, v172, v114
	v_fmac_f32_e32 v115, v229, v70
	v_fmac_f32_e32 v72, v228, v71
	v_fmac_f32_e32 v116, v228, v115
	v_fmac_f32_e32 v72, v172, v115
	v_fmac_f32_e32 v116, v229, v71
	v_fmac_f32_e32 v73, v228, v72
	v_fmac_f32_e32 v117, v228, v116
	v_fmac_f32_e32 v73, v172, v116
	v_fmac_f32_e32 v117, v229, v72
	v_fmac_f32_e32 v102, v228, v73
	v_fmac_f32_e32 v132, v228, v117
	v_fmac_f32_e32 v102, v172, v117
	v_fmac_f32_e32 v132, v229, v73
	v_fmac_f32_e32 v103, v228, v102
	v_fmac_f32_e32 v133, v228, v132
	v_fmac_f32_e32 v103, v172, v132
	v_fmac_f32_e32 v133, v229, v102
	v_fmac_f32_e32 v104, v228, v103
	v_fmac_f32_e32 v134, v228, v133
	v_fmac_f32_e32 v104, v172, v133
	v_fmac_f32_e32 v134, v229, v103
	v_fmac_f32_e32 v105, v228, v104
	v_fmac_f32_e32 v135, v228, v134
	v_fmac_f32_e32 v105, v172, v134
	v_fmac_f32_e32 v135, v229, v104
	v_fmac_f32_e32 v106, v228, v105
	v_fmac_f32_e32 v136, v228, v135
	v_fmac_f32_e32 v106, v172, v135
	v_fmac_f32_e32 v136, v229, v105
	v_fmac_f32_e32 v107, v228, v106
	v_fmac_f32_e32 v137, v228, v136
	v_fmac_f32_e32 v107, v172, v136
	v_fmac_f32_e32 v137, v229, v106
	v_fmac_f32_e32 v108, v228, v107
	v_fmac_f32_e32 v138, v228, v137
	v_fmac_f32_e32 v108, v172, v137
	v_fmac_f32_e32 v138, v229, v107
	v_fmac_f32_e32 v109, v228, v108
	v_fmac_f32_e32 v139, v228, v138
	v_fmac_f32_e32 v109, v172, v138
	v_fmac_f32_e32 v139, v229, v108
	v_fmac_f32_e32 v109, v230, v238
	v_fmac_f32_e32 v139, v230, v160
	v_fma_f32 v109, -v231, v160, v109
	v_fmac_f32_e32 v139, v231, v238
	v_mov_b32_e32 v238, v109
	v_mov_b32_e32 v160, v139
	s_nop 7
	v_fmac_f32_e32 v143, v232, v142
	v_fmac_f32_e32 v167, v232, v166
	v_fmac_f32_e32 v143, v173, v166
	v_fmac_f32_e32 v167, v233, v142
	v_fmac_f32_e32 v144, v232, v143
	v_fmac_f32_e32 v168, v232, v167
	v_fmac_f32_e32 v144, v173, v167
	v_fmac_f32_e32 v168, v233, v143
	v_fmac_f32_e32 v145, v232, v144
	v_fmac_f32_e32 v169, v232, v168
	v_fmac_f32_e32 v145, v173, v168
	v_fmac_f32_e32 v169, v233, v144
	v_fmac_f32_e32 v146, v232, v145
	v_fmac_f32_e32 v174, v232, v169
	v_fmac_f32_e32 v146, v173, v169
	v_fmac_f32_e32 v174, v233, v145
	v_fmac_f32_e32 v147, v232, v146
	v_fmac_f32_e32 v175, v232, v174
	v_fmac_f32_e32 v147, v173, v174
	v_fmac_f32_e32 v175, v233, v146
	v_fmac_f32_e32 v148, v232, v147
	v_fmac_f32_e32 v176, v232, v175
	v_fmac_f32_e32 v148, v173, v175
	v_fmac_f32_e32 v176, v233, v147
	v_fmac_f32_e32 v149, v232, v148
	v_fmac_f32_e32 v177, v232, v176
	v_fmac_f32_e32 v149, v173, v176
	v_fmac_f32_e32 v177, v233, v148
	v_fmac_f32_e32 v150, v232, v149
	v_fmac_f32_e32 v178, v232, v177
	v_fmac_f32_e32 v150, v173, v177
	v_fmac_f32_e32 v178, v233, v149
	v_fmac_f32_e32 v151, v232, v150
	v_fmac_f32_e32 v179, v232, v178
	v_fmac_f32_e32 v151, v173, v178
	v_fmac_f32_e32 v179, v233, v150
	v_fmac_f32_e32 v152, v232, v151
	v_fmac_f32_e32 v180, v232, v179
	v_fmac_f32_e32 v152, v173, v179
	v_fmac_f32_e32 v180, v233, v151
	v_fmac_f32_e32 v153, v232, v152
	v_fmac_f32_e32 v181, v232, v180
	v_fmac_f32_e32 v153, v173, v180
	v_fmac_f32_e32 v181, v233, v152
	v_fmac_f32_e32 v162, v232, v153
	v_fmac_f32_e32 v154, v232, v181
	v_fmac_f32_e32 v162, v173, v181
	v_fmac_f32_e32 v154, v233, v153
	v_fmac_f32_e32 v163, v232, v162
	v_fmac_f32_e32 v155, v232, v154
	v_fmac_f32_e32 v163, v173, v154
	v_fmac_f32_e32 v155, v233, v162
	v_fmac_f32_e32 v164, v232, v163
	v_fmac_f32_e32 v156, v232, v155
	v_fmac_f32_e32 v164, v173, v155
	v_fmac_f32_e32 v156, v233, v163
	v_fmac_f32_e32 v165, v232, v164
	v_fmac_f32_e32 v157, v232, v156
	v_fmac_f32_e32 v165, v173, v156
	v_fmac_f32_e32 v157, v233, v164
	v_fmac_f32_e32 v165, v234, v239
	v_fmac_f32_e32 v157, v234, v161
	v_fma_f32 v165, -v235, v161, v165
	v_fmac_f32_e32 v157, v235, v239
	v_mov_b32_e32 v239, v165
	v_mov_b32_e32 v161, v157
	s_add_u32 s24, s24, 0x90000
	s_addc_u32 s25, s25, 0
	s_cmp_lg_u32 s24, 0x240000
	s_cbranch_scc0 .Ls5p_fin0
	s_waitcnt vmcnt(0)
	v_mov_b64_e32 v[186:187], v[202:203]
	v_mov_b64_e32 v[188:189], v[204:205]
	v_mov_b64_e32 v[190:191], v[206:207]
	v_mov_b64_e32 v[192:193], v[208:209]
	v_mov_b64_e32 v[194:195], v[210:211]
	v_mov_b64_e32 v[196:197], v[212:213]
	v_mov_b64_e32 v[198:199], v[214:215]
	v_mov_b64_e32 v[200:201], v[216:217]
	s_branch .Ls5p_sb0
.Ls5p_fin0:
	v_mul_u32_u24_e32 v4, 0x4c, v3
	v_sub_u32_e32 v4, v130, v4
	ds_write_b32 v4, v236 offset:0
	ds_write_b32 v4, v158 offset:256
	ds_write_b32 v4, v237 offset:512
	ds_write_b32 v4, v159 offset:768
	ds_write_b32 v4, v238 offset:1024
	ds_write_b32 v4, v160 offset:1280
	ds_write_b32 v4, v239 offset:1536
	ds_write_b32 v4, v161 offset:1792
	v_lshrrev_b32_e32 v5, 4, v3
	v_sub_u32_e32 v4, v4, v3
	v_sub_u32_e32 v4, v4, v3
	v_sub_u32_e32 v4, v4, v3
	v_sub_u32_e32 v4, v4, v3
	v_lshl_add_u32 v4, v5, 9, v4
	v_add_u32_e32 v4, v131, v4
	s_waitcnt lgkmcnt(0)
	ds_read2_b32 v[62:63], v4 offset1:16
	ds_read2_b32 v[64:65], v4 offset0:32 offset1:48
	ds_read2_b32 v[66:67], v4 offset0:64 offset1:80
	ds_read2_b32 v[68:69], v4 offset0:96 offset1:112
	v_xor_b32_e32 v5, 0x80000000, v141
	s_waitcnt lgkmcnt(0)
	v_fmac_f32_e32 v63, v140, v62
	v_fmac_f32_e32 v67, v140, v66
	v_fmac_f32_e32 v63, v5, v66
	v_fmac_f32_e32 v67, v141, v62
	v_fmac_f32_e32 v64, v140, v63
	v_fmac_f32_e32 v68, v140, v67
	v_fmac_f32_e32 v64, v5, v67
	v_fmac_f32_e32 v68, v141, v63
	v_fmac_f32_e32 v65, v140, v64
	v_fmac_f32_e32 v69, v140, v68
	v_fmac_f32_e32 v65, v5, v68
	v_fmac_f32_e32 v69, v141, v64
	v_mov_b32_e32 v99, v65
	v_mov_b32_e32 v98, v69
	s_branch .LBB0_346
